# ResNorm epilogue: dropped 24 lgkmcnt(0) waits that only covered the preceding row-sum ds_write (drained before the barrier anyway)
# baseline (speedup 1.0000x reference)
;     __device__ __forceinline__ void operator()(const f32x4 (&acc)[2][2][4][2], const Unit& u, int wr, int wc, int fr, int fq) const {
;     ...
;             for (int m = 0; m < 4; ++m) { float q = 0.f;
; #pragma unroll
;                 for (int bj = 0; bj < 2; ++bj)
; #pragma unroll
;                     for (int n = 0; n < 2; ++n) { const f32x4 x = acc[ai][bj][m][n]; q += (x[0] * x[0] + x[1] * x[1]) + (x[2] * x[2] + x[3] * x[3]); }
;                 q += __shfl_xor(q, 16); q += __shfl_xor(q, 32);
;                 if (fq == 0) P[(rloc0 + ai * 128 + m * 16) * 4 + wc] = q; }
.LBB0_460:
	s_or_b64 exec, exec, s[54:55]
	v_mul_f32_e32 v176, v127, v127
	v_mul_f32_e32 v177, v129, v129
	v_fmac_f32_e32 v176, v126, v126
	v_fmac_f32_e32 v177, v128, v128
	v_add_f32_e32 v176, v176, v177
	v_mul_f32_e32 v177, v123, v123
	v_mul_f32_e32 v182, v125, v125
	v_fmac_f32_e32 v177, v122, v122
	v_fmac_f32_e32 v182, v124, v124
	v_add_f32_e32 v177, v177, v182
	v_add_f32_e32 v176, v176, v177
	v_mul_f32_e32 v177, v119, v119
	v_mul_f32_e32 v182, v121, v121
	v_fmac_f32_e32 v177, v118, v118
	v_fmac_f32_e32 v182, v120, v120
	v_add_f32_e32 v177, v177, v182
	v_add_f32_e32 v176, v176, v177
	v_mul_f32_e32 v177, v115, v115
	v_mul_f32_e32 v182, v117, v117
	v_fmac_f32_e32 v177, v114, v114
	v_fmac_f32_e32 v182, v116, v116
	v_add_f32_e32 v177, v177, v182
	v_add_f32_e32 v176, v176, v177
	v_mov_b32_e32 v177, v176
	s_nop 1
	v_permlane16_swap_b32_e32 v177, v176
	s_waitcnt lgkmcnt(0)
	v_add_f32_e32 v176, v176, v177
	v_mov_b32_e32 v177, v176
	s_nop 1
	v_permlane32_swap_b32_e32 v177, v176
	s_and_saveexec_b64 s[54:55], s[44:45]
	s_cbranch_execz .LBB0_462
	s_waitcnt lgkmcnt(0)
	v_add_f32_e32 v176, v176, v177
	ds_write_b32 v224, v176 offset:256
.LBB0_462:
	s_or_b64 exec, exec, s[54:55]
	v_mul_f32_e32 v176, v111, v111
	v_mul_f32_e32 v177, v113, v113
	v_fmac_f32_e32 v176, v110, v110
	v_fmac_f32_e32 v177, v112, v112
	v_add_f32_e32 v176, v176, v177
	v_mul_f32_e32 v177, v107, v107
	v_mul_f32_e32 v182, v109, v109
	v_fmac_f32_e32 v177, v106, v106
	v_fmac_f32_e32 v182, v108, v108
	v_add_f32_e32 v177, v177, v182
	v_add_f32_e32 v176, v176, v177
	v_mul_f32_e32 v177, v87, v87
	v_mul_f32_e32 v182, v89, v89
	v_fmac_f32_e32 v177, v86, v86
	v_fmac_f32_e32 v182, v88, v88
	v_add_f32_e32 v177, v177, v182
	v_add_f32_e32 v176, v176, v177
	v_mul_f32_e32 v177, v83, v83
	v_mul_f32_e32 v182, v85, v85
	v_fmac_f32_e32 v177, v82, v82
	v_fmac_f32_e32 v182, v84, v84
	v_add_f32_e32 v177, v177, v182
	v_add_f32_e32 v176, v176, v177
	v_mov_b32_e32 v177, v176
	s_nop 1
	v_permlane16_swap_b32_e32 v177, v176
	s_waitcnt lgkmcnt(0)
	v_add_f32_e32 v176, v176, v177
	v_mov_b32_e32 v177, v176
	s_nop 1
	v_permlane32_swap_b32_e32 v177, v176
	s_and_saveexec_b64 s[54:55], s[44:45]
	s_cbranch_execz .LBB0_464
	s_waitcnt lgkmcnt(0)
	v_add_f32_e32 v176, v176, v177
	ds_write_b32 v224, v176 offset:512
.LBB0_464:
	s_or_b64 exec, exec, s[54:55]
	v_mul_f32_e32 v176, v79, v79
	v_mul_f32_e32 v177, v81, v81
	v_fmac_f32_e32 v176, v78, v78
	v_fmac_f32_e32 v177, v80, v80
	v_add_f32_e32 v176, v176, v177
	v_mul_f32_e32 v177, v75, v75
	v_mul_f32_e32 v182, v77, v77
	v_fmac_f32_e32 v177, v74, v74
	v_fmac_f32_e32 v182, v76, v76
	v_add_f32_e32 v177, v177, v182
	v_add_f32_e32 v176, v176, v177
	v_mul_f32_e32 v177, v71, v71
	v_mul_f32_e32 v182, v73, v73
	v_fmac_f32_e32 v177, v70, v70
	v_fmac_f32_e32 v182, v72, v72
	v_add_f32_e32 v177, v177, v182
	v_add_f32_e32 v176, v176, v177
	v_mul_f32_e32 v177, v67, v67
	v_mul_f32_e32 v182, v69, v69
	v_fmac_f32_e32 v177, v66, v66
	v_fmac_f32_e32 v182, v68, v68
	v_add_f32_e32 v177, v177, v182
	v_add_f32_e32 v176, v176, v177
	v_mov_b32_e32 v177, v176
	s_nop 1
	v_permlane16_swap_b32_e32 v177, v176
	s_waitcnt lgkmcnt(0)
	v_add_f32_e32 v176, v176, v177
	v_mov_b32_e32 v177, v176
	s_nop 1
	v_permlane32_swap_b32_e32 v177, v176
	s_and_saveexec_b64 s[54:55], s[44:45]
	s_cbranch_execz .LBB0_466
	s_waitcnt lgkmcnt(0)
	v_add_f32_e32 v176, v176, v177
	ds_write_b32 v224, v176 offset:768
;     __device__ __forceinline__ void operator()(const f32x4 (&acc)[2][2][4][2], const Unit& u, int wr, int wc, int fr, int fq) const {
;     ...
;             for (int m = 0; m < 4; ++m) { float q = 0.f;
; #pragma unroll
;                 for (int bj = 0; bj < 2; ++bj)
; #pragma unroll
;                     for (int n = 0; n < 2; ++n) { const f32x4 x = acc[ai][bj][m][n]; q += (x[0] * x[0] + x[1] * x[1]) + (x[2] * x[2] + x[3] * x[3]); }
;                 q += __shfl_xor(q, 16); q += __shfl_xor(q, 32);
;                 if (fq == 0) P[(rloc0 + ai * 128 + m * 16) * 4 + wc] = q; }
.LBB0_466:
	s_or_b64 exec, exec, s[54:55]
	v_mul_f32_e32 v176, v63, v63
	v_mul_f32_e32 v177, v65, v65
	v_fmac_f32_e32 v176, v62, v62
	v_fmac_f32_e32 v177, v64, v64
	v_add_f32_e32 v176, v176, v177
	v_mul_f32_e32 v177, v59, v59
	v_mul_f32_e32 v182, v61, v61
	v_fmac_f32_e32 v177, v58, v58
	v_fmac_f32_e32 v182, v60, v60
	v_add_f32_e32 v177, v177, v182
	v_add_f32_e32 v176, v176, v177
	v_mul_f32_e32 v177, v55, v55
	v_mul_f32_e32 v182, v57, v57
	v_fmac_f32_e32 v177, v54, v54
	v_fmac_f32_e32 v182, v56, v56
	v_add_f32_e32 v177, v177, v182
	v_add_f32_e32 v176, v176, v177
	v_mul_f32_e32 v177, v51, v51
	v_mul_f32_e32 v182, v53, v53
	v_fmac_f32_e32 v177, v50, v50
	v_fmac_f32_e32 v182, v52, v52
	v_add_f32_e32 v177, v177, v182
	v_add_f32_e32 v176, v176, v177
	v_mov_b32_e32 v177, v176
	s_nop 1
	v_permlane16_swap_b32_e32 v177, v176
	s_waitcnt lgkmcnt(0)
	v_add_f32_e32 v176, v176, v177
	v_mov_b32_e32 v177, v176
	s_nop 1
	v_permlane32_swap_b32_e32 v177, v176
	s_and_saveexec_b64 s[54:55], s[44:45]
	s_cbranch_execz .LBB0_468
	s_waitcnt lgkmcnt(0)
	v_add_f32_e32 v176, v176, v177
	ds_write_b32 v224, v176 offset:2048
.LBB0_468:
	s_or_b64 exec, exec, s[54:55]
	v_mul_f32_e32 v176, v47, v47
	v_mul_f32_e32 v177, v49, v49
	v_fmac_f32_e32 v176, v46, v46
	v_fmac_f32_e32 v177, v48, v48
	v_add_f32_e32 v176, v176, v177
	v_mul_f32_e32 v177, v43, v43
	v_mul_f32_e32 v182, v45, v45
	v_fmac_f32_e32 v177, v42, v42
	v_fmac_f32_e32 v182, v44, v44
	v_add_f32_e32 v177, v177, v182
	v_add_f32_e32 v176, v176, v177
	v_mul_f32_e32 v177, v39, v39
	v_mul_f32_e32 v182, v41, v41
	v_fmac_f32_e32 v177, v38, v38
	v_fmac_f32_e32 v182, v40, v40
	v_add_f32_e32 v177, v177, v182
	v_add_f32_e32 v176, v176, v177
	v_mul_f32_e32 v177, v35, v35
	v_mul_f32_e32 v182, v37, v37
	v_fmac_f32_e32 v177, v34, v34
	v_fmac_f32_e32 v182, v36, v36
	v_add_f32_e32 v177, v177, v182
	v_add_f32_e32 v176, v176, v177
	v_mov_b32_e32 v177, v176
	s_nop 1
	v_permlane16_swap_b32_e32 v177, v176
	s_waitcnt lgkmcnt(0)
	v_add_f32_e32 v176, v176, v177
	v_mov_b32_e32 v177, v176
	s_nop 1
	v_permlane32_swap_b32_e32 v177, v176
	s_and_saveexec_b64 s[54:55], s[44:45]
	s_cbranch_execz .LBB0_470
	s_waitcnt lgkmcnt(0)
	v_add_f32_e32 v176, v176, v177
	ds_write_b32 v224, v176 offset:2304
.LBB0_470:
	s_or_b64 exec, exec, s[54:55]
	v_mul_f32_e32 v176, v31, v31
	v_mul_f32_e32 v177, v33, v33
	v_fmac_f32_e32 v176, v30, v30
	v_fmac_f32_e32 v177, v32, v32
	v_add_f32_e32 v176, v176, v177
	v_mul_f32_e32 v177, v27, v27
	v_mul_f32_e32 v182, v29, v29
	v_fmac_f32_e32 v177, v26, v26
	v_fmac_f32_e32 v182, v28, v28
	v_add_f32_e32 v177, v177, v182
	v_add_f32_e32 v176, v176, v177
	v_mul_f32_e32 v177, v23, v23
	v_mul_f32_e32 v182, v25, v25
	v_fmac_f32_e32 v177, v22, v22
	v_fmac_f32_e32 v182, v24, v24
	v_add_f32_e32 v177, v177, v182
	v_add_f32_e32 v176, v176, v177
	v_mul_f32_e32 v177, v19, v19
	v_mul_f32_e32 v182, v21, v21
	v_fmac_f32_e32 v177, v18, v18
	v_fmac_f32_e32 v182, v20, v20
	v_add_f32_e32 v177, v177, v182
	v_add_f32_e32 v176, v176, v177
	v_mov_b32_e32 v177, v176
	s_nop 1
	v_permlane16_swap_b32_e32 v177, v176
	s_waitcnt lgkmcnt(0)
	v_add_f32_e32 v176, v176, v177
	v_mov_b32_e32 v177, v176
	s_nop 1
	v_permlane32_swap_b32_e32 v177, v176
	s_and_saveexec_b64 s[54:55], s[44:45]
	s_cbranch_execz .LBB0_472
	s_waitcnt lgkmcnt(0)
	v_add_f32_e32 v176, v176, v177
	ds_write_b32 v224, v176 offset:2560
.LBB0_472:
	s_or_b64 exec, exec, s[54:55]
	v_mul_f32_e32 v176, v15, v15
	v_mul_f32_e32 v177, v17, v17
	v_fmac_f32_e32 v176, v14, v14
	v_fmac_f32_e32 v177, v16, v16
	v_add_f32_e32 v176, v176, v177
	v_mul_f32_e32 v177, v11, v11
	v_mul_f32_e32 v182, v13, v13
	v_fmac_f32_e32 v177, v10, v10
	v_fmac_f32_e32 v182, v12, v12
	v_add_f32_e32 v177, v177, v182
	v_add_f32_e32 v176, v176, v177
	v_mul_f32_e32 v177, v7, v7
	v_mul_f32_e32 v182, v9, v9
	v_fmac_f32_e32 v177, v6, v6
	v_fmac_f32_e32 v182, v8, v8
	v_add_f32_e32 v177, v177, v182
	v_add_f32_e32 v176, v176, v177
	v_mul_f32_e32 v177, v3, v3
	v_mul_f32_e32 v182, v5, v5
	v_fmac_f32_e32 v177, v2, v2
	v_fmac_f32_e32 v182, v4, v4
	v_add_f32_e32 v177, v177, v182
	v_add_f32_e32 v176, v176, v177
	v_mov_b32_e32 v177, v176
	s_nop 1
	v_permlane16_swap_b32_e32 v177, v176
	s_waitcnt lgkmcnt(0)
	v_add_f32_e32 v176, v176, v177
	v_mov_b32_e32 v177, v176
	s_nop 1
	v_permlane32_swap_b32_e32 v177, v176
	s_and_saveexec_b64 s[54:55], s[44:45]
	s_cbranch_execz .LBB0_474
	s_waitcnt lgkmcnt(0)
	v_add_f32_e32 v176, v176, v177
	ds_write_b32 v224, v176 offset:2816

;     __device__ __forceinline__ void operator()(const f32x4 (&acc)[2][2][4][2], const Unit& u, int wr, int wc, int fr, int fq) const {
;     ...
;             for (int m = 0; m < 4; ++m) { float q = 0.f;
; #pragma unroll
;                 for (int bj = 0; bj < 2; ++bj)
; #pragma unroll
;                     for (int n = 0; n < 2; ++n) { const f32x4 x = acc[ai][bj][m][n]; q += (x[0] * x[0] + x[1] * x[1]) + (x[2] * x[2] + x[3] * x[3]); }
;                 q += __shfl_xor(q, 16); q += __shfl_xor(q, 32);
;                 if (fq == 0) P[(rloc0 + ai * 128 + m * 16) * 4 + wc] = q; }
.LBB0_1142:
	s_or_b64 exec, exec, s[14:15]
	v_mul_f32_e32 v176, v127, v127
	v_mul_f32_e32 v177, v129, v129
	v_fmac_f32_e32 v176, v126, v126
	v_fmac_f32_e32 v177, v128, v128
	v_add_f32_e32 v176, v176, v177
	v_mul_f32_e32 v177, v123, v123
	v_mul_f32_e32 v182, v125, v125
	v_fmac_f32_e32 v177, v122, v122
	v_fmac_f32_e32 v182, v124, v124
	v_add_f32_e32 v177, v177, v182
	v_add_f32_e32 v176, v176, v177
	v_mul_f32_e32 v177, v119, v119
	v_mul_f32_e32 v182, v121, v121
	v_fmac_f32_e32 v177, v118, v118
	v_fmac_f32_e32 v182, v120, v120
	v_add_f32_e32 v177, v177, v182
	v_add_f32_e32 v176, v176, v177
	v_mul_f32_e32 v177, v115, v115
	v_mul_f32_e32 v182, v117, v117
	v_fmac_f32_e32 v177, v114, v114
	v_fmac_f32_e32 v182, v116, v116
	v_add_f32_e32 v177, v177, v182
	v_add_f32_e32 v176, v176, v177
	v_mov_b32_e32 v177, v176
	s_nop 1
	v_permlane16_swap_b32_e32 v177, v176
	s_waitcnt lgkmcnt(0)
	v_add_f32_e32 v176, v176, v177
	v_mov_b32_e32 v177, v176
	s_nop 1
	v_permlane32_swap_b32_e32 v177, v176
	s_and_saveexec_b64 s[14:15], s[42:43]
	s_cbranch_execz .LBB0_1144
	s_waitcnt lgkmcnt(0)
	v_add_f32_e32 v176, v176, v177
	ds_write_b32 v224, v176 offset:256
.LBB0_1144:
	s_or_b64 exec, exec, s[14:15]
	v_mul_f32_e32 v176, v111, v111
	v_mul_f32_e32 v177, v113, v113
	v_fmac_f32_e32 v176, v110, v110
	v_fmac_f32_e32 v177, v112, v112
	v_add_f32_e32 v176, v176, v177
	v_mul_f32_e32 v177, v107, v107
	v_mul_f32_e32 v182, v109, v109
	v_fmac_f32_e32 v177, v106, v106
	v_fmac_f32_e32 v182, v108, v108
	v_add_f32_e32 v177, v177, v182
	v_add_f32_e32 v176, v176, v177
	v_mul_f32_e32 v177, v87, v87
	v_mul_f32_e32 v182, v89, v89
	v_fmac_f32_e32 v177, v86, v86
	v_fmac_f32_e32 v182, v88, v88
	v_add_f32_e32 v177, v177, v182
	v_add_f32_e32 v176, v176, v177
	v_mul_f32_e32 v177, v83, v83
	v_mul_f32_e32 v182, v85, v85
	v_fmac_f32_e32 v177, v82, v82
	v_fmac_f32_e32 v182, v84, v84
	v_add_f32_e32 v177, v177, v182
	v_add_f32_e32 v176, v176, v177
	v_mov_b32_e32 v177, v176
	s_nop 1
	v_permlane16_swap_b32_e32 v177, v176
	s_waitcnt lgkmcnt(0)
	v_add_f32_e32 v176, v176, v177
	v_mov_b32_e32 v177, v176
	s_nop 1
	v_permlane32_swap_b32_e32 v177, v176
	s_and_saveexec_b64 s[14:15], s[42:43]
	s_cbranch_execz .LBB0_1146
	s_waitcnt lgkmcnt(0)
	v_add_f32_e32 v176, v176, v177
	ds_write_b32 v224, v176 offset:512
.LBB0_1146:
	s_or_b64 exec, exec, s[14:15]
	v_mul_f32_e32 v176, v79, v79
	v_mul_f32_e32 v177, v81, v81
	v_fmac_f32_e32 v176, v78, v78
	v_fmac_f32_e32 v177, v80, v80
	v_add_f32_e32 v176, v176, v177
	v_mul_f32_e32 v177, v75, v75
	v_mul_f32_e32 v182, v77, v77
	v_fmac_f32_e32 v177, v74, v74
	v_fmac_f32_e32 v182, v76, v76
	v_add_f32_e32 v177, v177, v182
	v_add_f32_e32 v176, v176, v177
	v_mul_f32_e32 v177, v71, v71
	v_mul_f32_e32 v182, v73, v73
	v_fmac_f32_e32 v177, v70, v70
	v_fmac_f32_e32 v182, v72, v72
	v_add_f32_e32 v177, v177, v182
	v_add_f32_e32 v176, v176, v177
	v_mul_f32_e32 v177, v67, v67
	v_mul_f32_e32 v182, v69, v69
	v_fmac_f32_e32 v177, v66, v66
	v_fmac_f32_e32 v182, v68, v68
	v_add_f32_e32 v177, v177, v182
	v_add_f32_e32 v176, v176, v177
	v_mov_b32_e32 v177, v176
	s_nop 1
	v_permlane16_swap_b32_e32 v177, v176
	s_waitcnt lgkmcnt(0)
	v_add_f32_e32 v176, v176, v177
	v_mov_b32_e32 v177, v176
	s_nop 1
	v_permlane32_swap_b32_e32 v177, v176
	s_and_saveexec_b64 s[14:15], s[42:43]
	s_cbranch_execz .LBB0_1148
	s_waitcnt lgkmcnt(0)
	v_add_f32_e32 v176, v176, v177
	ds_write_b32 v224, v176 offset:768
;     __device__ __forceinline__ void operator()(const f32x4 (&acc)[2][2][4][2], const Unit& u, int wr, int wc, int fr, int fq) const {
;     ...
;             for (int m = 0; m < 4; ++m) { float q = 0.f;
; #pragma unroll
;                 for (int bj = 0; bj < 2; ++bj)
; #pragma unroll
;                     for (int n = 0; n < 2; ++n) { const f32x4 x = acc[ai][bj][m][n]; q += (x[0] * x[0] + x[1] * x[1]) + (x[2] * x[2] + x[3] * x[3]); }
;                 q += __shfl_xor(q, 16); q += __shfl_xor(q, 32);
;                 if (fq == 0) P[(rloc0 + ai * 128 + m * 16) * 4 + wc] = q; }
.LBB0_1148:
	s_or_b64 exec, exec, s[14:15]
	v_mul_f32_e32 v176, v63, v63
	v_mul_f32_e32 v177, v65, v65
	v_fmac_f32_e32 v176, v62, v62
	v_fmac_f32_e32 v177, v64, v64
	v_add_f32_e32 v176, v176, v177
	v_mul_f32_e32 v177, v59, v59
	v_mul_f32_e32 v182, v61, v61
	v_fmac_f32_e32 v177, v58, v58
	v_fmac_f32_e32 v182, v60, v60
	v_add_f32_e32 v177, v177, v182
	v_add_f32_e32 v176, v176, v177
	v_mul_f32_e32 v177, v55, v55
	v_mul_f32_e32 v182, v57, v57
	v_fmac_f32_e32 v177, v54, v54
	v_fmac_f32_e32 v182, v56, v56
	v_add_f32_e32 v177, v177, v182
	v_add_f32_e32 v176, v176, v177
	v_mul_f32_e32 v177, v51, v51
	v_mul_f32_e32 v182, v53, v53
	v_fmac_f32_e32 v177, v50, v50
	v_fmac_f32_e32 v182, v52, v52
	v_add_f32_e32 v177, v177, v182
	v_add_f32_e32 v176, v176, v177
	v_mov_b32_e32 v177, v176
	s_nop 1
	v_permlane16_swap_b32_e32 v177, v176
	s_waitcnt lgkmcnt(0)
	v_add_f32_e32 v176, v176, v177
	v_mov_b32_e32 v177, v176
	s_nop 1
	v_permlane32_swap_b32_e32 v177, v176
	s_and_saveexec_b64 s[14:15], s[42:43]
	s_cbranch_execz .LBB0_1150
	s_waitcnt lgkmcnt(0)
	v_add_f32_e32 v176, v176, v177
	ds_write_b32 v224, v176 offset:2048
.LBB0_1150:
	s_or_b64 exec, exec, s[14:15]
	v_mul_f32_e32 v176, v47, v47
	v_mul_f32_e32 v177, v49, v49
	v_fmac_f32_e32 v176, v46, v46
	v_fmac_f32_e32 v177, v48, v48
	v_add_f32_e32 v176, v176, v177
	v_mul_f32_e32 v177, v43, v43
	v_mul_f32_e32 v182, v45, v45
	v_fmac_f32_e32 v177, v42, v42
	v_fmac_f32_e32 v182, v44, v44
	v_add_f32_e32 v177, v177, v182
	v_add_f32_e32 v176, v176, v177
	v_mul_f32_e32 v177, v39, v39
	v_mul_f32_e32 v182, v41, v41
	v_fmac_f32_e32 v177, v38, v38
	v_fmac_f32_e32 v182, v40, v40
	v_add_f32_e32 v177, v177, v182
	v_add_f32_e32 v176, v176, v177
	v_mul_f32_e32 v177, v35, v35
	v_mul_f32_e32 v182, v37, v37
	v_fmac_f32_e32 v177, v34, v34
	v_fmac_f32_e32 v182, v36, v36
	v_add_f32_e32 v177, v177, v182
	v_add_f32_e32 v176, v176, v177
	v_mov_b32_e32 v177, v176
	s_nop 1
	v_permlane16_swap_b32_e32 v177, v176
	s_waitcnt lgkmcnt(0)
	v_add_f32_e32 v176, v176, v177
	v_mov_b32_e32 v177, v176
	s_nop 1
	v_permlane32_swap_b32_e32 v177, v176
	s_and_saveexec_b64 s[14:15], s[42:43]
	s_cbranch_execz .LBB0_1152
	s_waitcnt lgkmcnt(0)
	v_add_f32_e32 v176, v176, v177
	ds_write_b32 v224, v176 offset:2304
.LBB0_1152:
	s_or_b64 exec, exec, s[14:15]
	v_mul_f32_e32 v176, v31, v31
	v_mul_f32_e32 v177, v33, v33
	v_fmac_f32_e32 v176, v30, v30
	v_fmac_f32_e32 v177, v32, v32
	v_add_f32_e32 v176, v176, v177
	v_mul_f32_e32 v177, v27, v27
	v_mul_f32_e32 v182, v29, v29
	v_fmac_f32_e32 v177, v26, v26
	v_fmac_f32_e32 v182, v28, v28
	v_add_f32_e32 v177, v177, v182
	v_add_f32_e32 v176, v176, v177
	v_mul_f32_e32 v177, v23, v23
	v_mul_f32_e32 v182, v25, v25
	v_fmac_f32_e32 v177, v22, v22
	v_fmac_f32_e32 v182, v24, v24
	v_add_f32_e32 v177, v177, v182
	v_add_f32_e32 v176, v176, v177
	v_mul_f32_e32 v177, v19, v19
	v_mul_f32_e32 v182, v21, v21
	v_fmac_f32_e32 v177, v18, v18
	v_fmac_f32_e32 v182, v20, v20
	v_add_f32_e32 v177, v177, v182
	v_add_f32_e32 v176, v176, v177
	v_mov_b32_e32 v177, v176
	s_nop 1
	v_permlane16_swap_b32_e32 v177, v176
	s_waitcnt lgkmcnt(0)
	v_add_f32_e32 v176, v176, v177
	v_mov_b32_e32 v177, v176
	s_nop 1
	v_permlane32_swap_b32_e32 v177, v176
	s_and_saveexec_b64 s[14:15], s[42:43]
	s_cbranch_execz .LBB0_1154
	s_waitcnt lgkmcnt(0)
	v_add_f32_e32 v176, v176, v177
	ds_write_b32 v224, v176 offset:2560
.LBB0_1154:
	s_or_b64 exec, exec, s[14:15]
	v_mul_f32_e32 v176, v15, v15
	v_mul_f32_e32 v177, v17, v17
	v_fmac_f32_e32 v176, v14, v14
	v_fmac_f32_e32 v177, v16, v16
	v_add_f32_e32 v176, v176, v177
	v_mul_f32_e32 v177, v11, v11
	v_mul_f32_e32 v182, v13, v13
	v_fmac_f32_e32 v177, v10, v10
	v_fmac_f32_e32 v182, v12, v12
	v_add_f32_e32 v177, v177, v182
	v_add_f32_e32 v176, v176, v177
	v_mul_f32_e32 v177, v7, v7
	v_mul_f32_e32 v182, v9, v9
	v_fmac_f32_e32 v177, v6, v6
	v_fmac_f32_e32 v182, v8, v8
	v_add_f32_e32 v177, v177, v182
	v_add_f32_e32 v176, v176, v177
	v_mul_f32_e32 v177, v3, v3
	v_mul_f32_e32 v182, v5, v5
	v_fmac_f32_e32 v177, v2, v2
	v_fmac_f32_e32 v182, v4, v4
	v_add_f32_e32 v177, v177, v182
	v_add_f32_e32 v176, v176, v177
	v_mov_b32_e32 v177, v176
	s_nop 1
	v_permlane16_swap_b32_e32 v177, v176
	s_waitcnt lgkmcnt(0)
	v_add_f32_e32 v176, v176, v177
	v_mov_b32_e32 v177, v176
	s_nop 1
	v_permlane32_swap_b32_e32 v177, v176
	s_and_saveexec_b64 s[14:15], s[42:43]
	s_cbranch_execz .LBB0_1156
	s_waitcnt lgkmcnt(0)
	v_add_f32_e32 v176, v176, v177
	ds_write_b32 v224, v176 offset:2816

;     __device__ __forceinline__ void operator()(const f32x4 (&acc)[2][2][4][2], const Unit& u, int wr, int wc, int fr, int fq) const {
;     ...
;             for (int m = 0; m < 4; ++m) { float q = 0.f;
; #pragma unroll
;                 for (int bj = 0; bj < 2; ++bj)
; #pragma unroll
;                     for (int n = 0; n < 2; ++n) { const f32x4 x = acc[ai][bj][m][n]; q += (x[0] * x[0] + x[1] * x[1]) + (x[2] * x[2] + x[3] * x[3]); }
;                 q += __shfl_xor(q, 16); q += __shfl_xor(q, 32);
;                 if (fq == 0) P[(rloc0 + ai * 128 + m * 16) * 4 + wc] = q; }
.LBB0_1320:
	s_or_b64 exec, exec, s[34:35]
	v_mul_f32_e32 v164, v127, v127
	v_mul_f32_e32 v165, v129, v129
	v_fmac_f32_e32 v164, v126, v126
	v_fmac_f32_e32 v165, v128, v128
	v_add_f32_e32 v164, v164, v165
	v_mul_f32_e32 v165, v123, v123
	v_mul_f32_e32 v170, v125, v125
	v_fmac_f32_e32 v165, v122, v122
	v_fmac_f32_e32 v170, v124, v124
	v_add_f32_e32 v165, v165, v170
	v_add_f32_e32 v164, v164, v165
	v_mul_f32_e32 v165, v119, v119
	v_mul_f32_e32 v170, v121, v121
	v_fmac_f32_e32 v165, v118, v118
	v_fmac_f32_e32 v170, v120, v120
	v_add_f32_e32 v165, v165, v170
	v_add_f32_e32 v164, v164, v165
	v_mul_f32_e32 v165, v115, v115
	v_mul_f32_e32 v170, v117, v117
	v_fmac_f32_e32 v165, v114, v114
	v_fmac_f32_e32 v170, v116, v116
	v_add_f32_e32 v165, v165, v170
	v_add_f32_e32 v164, v164, v165
	v_mov_b32_e32 v165, v164
	s_nop 1
	v_permlane16_swap_b32_e32 v165, v164
	s_waitcnt lgkmcnt(0)
	v_add_f32_e32 v164, v164, v165
	v_mov_b32_e32 v165, v164
	s_nop 1
	v_permlane32_swap_b32_e32 v165, v164
	s_and_saveexec_b64 s[34:35], s[42:43]
	s_cbranch_execz .LBB0_1322
	s_waitcnt lgkmcnt(0)
	v_add_f32_e32 v164, v164, v165
	ds_write_b32 v230, v164 offset:256
.LBB0_1322:
	s_or_b64 exec, exec, s[34:35]
	v_mul_f32_e32 v164, v111, v111
	v_mul_f32_e32 v165, v113, v113
	v_fmac_f32_e32 v164, v110, v110
	v_fmac_f32_e32 v165, v112, v112
	v_add_f32_e32 v164, v164, v165
	v_mul_f32_e32 v165, v107, v107
	v_mul_f32_e32 v170, v109, v109
	v_fmac_f32_e32 v165, v106, v106
	v_fmac_f32_e32 v170, v108, v108
	v_add_f32_e32 v165, v165, v170
	v_add_f32_e32 v164, v164, v165
	v_mul_f32_e32 v165, v103, v103
	v_mul_f32_e32 v170, v105, v105
	v_fmac_f32_e32 v165, v102, v102
	v_fmac_f32_e32 v170, v104, v104
	v_add_f32_e32 v165, v165, v170
	v_add_f32_e32 v164, v164, v165
	v_mul_f32_e32 v165, v99, v99
	v_mul_f32_e32 v170, v101, v101
	v_fmac_f32_e32 v165, v98, v98
	v_fmac_f32_e32 v170, v100, v100
	v_add_f32_e32 v165, v165, v170
	v_add_f32_e32 v164, v164, v165
	v_mov_b32_e32 v165, v164
	s_nop 1
	v_permlane16_swap_b32_e32 v165, v164
	s_waitcnt lgkmcnt(0)
	v_add_f32_e32 v164, v164, v165
	v_mov_b32_e32 v165, v164
	s_nop 1
	v_permlane32_swap_b32_e32 v165, v164
	s_and_saveexec_b64 s[34:35], s[42:43]
	s_cbranch_execz .LBB0_1324
	s_waitcnt lgkmcnt(0)
	v_add_f32_e32 v164, v164, v165
	ds_write_b32 v230, v164 offset:512
.LBB0_1324:
	s_or_b64 exec, exec, s[34:35]
	v_mul_f32_e32 v164, v95, v95
	v_mul_f32_e32 v165, v97, v97
	v_fmac_f32_e32 v164, v94, v94
	v_fmac_f32_e32 v165, v96, v96
	v_add_f32_e32 v164, v164, v165
	v_mul_f32_e32 v165, v91, v91
	v_mul_f32_e32 v170, v93, v93
	v_fmac_f32_e32 v165, v90, v90
	v_fmac_f32_e32 v170, v92, v92
	v_add_f32_e32 v165, v165, v170
	v_add_f32_e32 v164, v164, v165
	v_mul_f32_e32 v165, v87, v87
	v_mul_f32_e32 v170, v89, v89
	v_fmac_f32_e32 v165, v86, v86
	v_fmac_f32_e32 v170, v88, v88
	v_add_f32_e32 v165, v165, v170
	v_add_f32_e32 v164, v164, v165
	v_mul_f32_e32 v165, v83, v83
	v_mul_f32_e32 v170, v85, v85
	v_fmac_f32_e32 v165, v82, v82
	v_fmac_f32_e32 v170, v84, v84
	v_add_f32_e32 v165, v165, v170
	v_add_f32_e32 v164, v164, v165
	v_mov_b32_e32 v165, v164
	s_nop 1
	v_permlane16_swap_b32_e32 v165, v164
	s_waitcnt lgkmcnt(0)
	v_add_f32_e32 v164, v164, v165
	v_mov_b32_e32 v165, v164
	s_nop 1
	v_permlane32_swap_b32_e32 v165, v164
	s_and_saveexec_b64 s[34:35], s[42:43]
	s_cbranch_execz .LBB0_1326
	s_waitcnt lgkmcnt(0)
	v_add_f32_e32 v164, v164, v165
	ds_write_b32 v230, v164 offset:768
;     __device__ __forceinline__ void operator()(const f32x4 (&acc)[2][2][4][2], const Unit& u, int wr, int wc, int fr, int fq) const {
;     ...
;             for (int m = 0; m < 4; ++m) { float q = 0.f;
; #pragma unroll
;                 for (int bj = 0; bj < 2; ++bj)
; #pragma unroll
;                     for (int n = 0; n < 2; ++n) { const f32x4 x = acc[ai][bj][m][n]; q += (x[0] * x[0] + x[1] * x[1]) + (x[2] * x[2] + x[3] * x[3]); }
;                 q += __shfl_xor(q, 16); q += __shfl_xor(q, 32);
;                 if (fq == 0) P[(rloc0 + ai * 128 + m * 16) * 4 + wc] = q; }
.LBB0_1326:
	s_or_b64 exec, exec, s[34:35]
	v_mul_f32_e32 v164, v71, v71
	v_mul_f32_e32 v165, v73, v73
	v_fmac_f32_e32 v164, v70, v70
	v_fmac_f32_e32 v165, v72, v72
	v_add_f32_e32 v164, v164, v165
	v_mul_f32_e32 v165, v67, v67
	v_mul_f32_e32 v170, v69, v69
	v_fmac_f32_e32 v165, v66, v66
	v_fmac_f32_e32 v170, v68, v68
	v_add_f32_e32 v165, v165, v170
	v_add_f32_e32 v164, v164, v165
	v_mul_f32_e32 v165, v55, v55
	v_mul_f32_e32 v170, v57, v57
	v_fmac_f32_e32 v165, v54, v54
	v_fmac_f32_e32 v170, v56, v56
	v_add_f32_e32 v165, v165, v170
	v_add_f32_e32 v164, v164, v165
	v_mul_f32_e32 v165, v51, v51
	v_mul_f32_e32 v170, v53, v53
	v_fmac_f32_e32 v165, v50, v50
	v_fmac_f32_e32 v170, v52, v52
	v_add_f32_e32 v165, v165, v170
	v_add_f32_e32 v164, v164, v165
	v_mov_b32_e32 v165, v164
	s_nop 1
	v_permlane16_swap_b32_e32 v165, v164
	s_waitcnt lgkmcnt(0)
	v_add_f32_e32 v164, v164, v165
	v_mov_b32_e32 v165, v164
	s_nop 1
	v_permlane32_swap_b32_e32 v165, v164
	s_and_saveexec_b64 s[34:35], s[42:43]
	s_cbranch_execz .LBB0_1328
	s_waitcnt lgkmcnt(0)
	v_add_f32_e32 v164, v164, v165
	ds_write_b32 v230, v164 offset:2048
.LBB0_1328:
	s_or_b64 exec, exec, s[34:35]
	v_mul_f32_e32 v164, v47, v47
	v_mul_f32_e32 v165, v49, v49
	v_fmac_f32_e32 v164, v46, v46
	v_fmac_f32_e32 v165, v48, v48
	v_add_f32_e32 v164, v164, v165
	v_mul_f32_e32 v165, v43, v43
	v_mul_f32_e32 v170, v45, v45
	v_fmac_f32_e32 v165, v42, v42
	v_fmac_f32_e32 v170, v44, v44
	v_add_f32_e32 v165, v165, v170
	v_add_f32_e32 v164, v164, v165
	v_mul_f32_e32 v165, v39, v39
	v_mul_f32_e32 v170, v41, v41
	v_fmac_f32_e32 v165, v38, v38
	v_fmac_f32_e32 v170, v40, v40
	v_add_f32_e32 v165, v165, v170
	v_add_f32_e32 v164, v164, v165
	v_mul_f32_e32 v165, v35, v35
	v_mul_f32_e32 v170, v37, v37
	v_fmac_f32_e32 v165, v34, v34
	v_fmac_f32_e32 v170, v36, v36
	v_add_f32_e32 v165, v165, v170
	v_add_f32_e32 v164, v164, v165
	v_mov_b32_e32 v165, v164
	s_nop 1
	v_permlane16_swap_b32_e32 v165, v164
	s_waitcnt lgkmcnt(0)
	v_add_f32_e32 v164, v164, v165
	v_mov_b32_e32 v165, v164
	s_nop 1
	v_permlane32_swap_b32_e32 v165, v164
	s_and_saveexec_b64 s[34:35], s[42:43]
	s_cbranch_execz .LBB0_1330
	s_waitcnt lgkmcnt(0)
	v_add_f32_e32 v164, v164, v165
	ds_write_b32 v230, v164 offset:2304
.LBB0_1330:
	s_or_b64 exec, exec, s[34:35]
	v_mul_f32_e32 v164, v31, v31
	v_mul_f32_e32 v165, v33, v33
	v_fmac_f32_e32 v164, v30, v30
	v_fmac_f32_e32 v165, v32, v32
	v_add_f32_e32 v164, v164, v165
	v_mul_f32_e32 v165, v27, v27
	v_mul_f32_e32 v170, v29, v29
	v_fmac_f32_e32 v165, v26, v26
	v_fmac_f32_e32 v170, v28, v28
	v_add_f32_e32 v165, v165, v170
	v_add_f32_e32 v164, v164, v165
	v_mul_f32_e32 v165, v23, v23
	v_mul_f32_e32 v170, v25, v25
	v_fmac_f32_e32 v165, v22, v22
	v_fmac_f32_e32 v170, v24, v24
	v_add_f32_e32 v165, v165, v170
	v_add_f32_e32 v164, v164, v165
	v_mul_f32_e32 v165, v19, v19
	v_mul_f32_e32 v170, v21, v21
	v_fmac_f32_e32 v165, v18, v18
	v_fmac_f32_e32 v170, v20, v20
	v_add_f32_e32 v165, v165, v170
	v_add_f32_e32 v164, v164, v165
	v_mov_b32_e32 v165, v164
	s_nop 1
	v_permlane16_swap_b32_e32 v165, v164
	s_waitcnt lgkmcnt(0)
	v_add_f32_e32 v164, v164, v165
	v_mov_b32_e32 v165, v164
	s_nop 1
	v_permlane32_swap_b32_e32 v165, v164
	s_and_saveexec_b64 s[34:35], s[42:43]
	s_cbranch_execz .LBB0_1332
	s_waitcnt lgkmcnt(0)
	v_add_f32_e32 v164, v164, v165
	ds_write_b32 v230, v164 offset:2560
.LBB0_1332:
	s_or_b64 exec, exec, s[34:35]
	v_mul_f32_e32 v164, v15, v15
	v_mul_f32_e32 v165, v17, v17
	v_fmac_f32_e32 v164, v14, v14
	v_fmac_f32_e32 v165, v16, v16
	v_add_f32_e32 v164, v164, v165
	v_mul_f32_e32 v165, v11, v11
	v_mul_f32_e32 v170, v13, v13
	v_fmac_f32_e32 v165, v10, v10
	v_fmac_f32_e32 v170, v12, v12
	v_add_f32_e32 v165, v165, v170
	v_add_f32_e32 v164, v164, v165
	v_mul_f32_e32 v165, v7, v7
	v_mul_f32_e32 v170, v9, v9
	v_fmac_f32_e32 v165, v6, v6
	v_fmac_f32_e32 v170, v8, v8
	v_add_f32_e32 v165, v165, v170
	v_add_f32_e32 v164, v164, v165
	v_mul_f32_e32 v165, v3, v3
	v_mul_f32_e32 v170, v5, v5
	v_fmac_f32_e32 v165, v2, v2
	v_fmac_f32_e32 v170, v4, v4
	v_add_f32_e32 v165, v165, v170
	v_add_f32_e32 v164, v164, v165
	v_mov_b32_e32 v165, v164
	s_nop 1
	v_permlane16_swap_b32_e32 v165, v164
	s_waitcnt lgkmcnt(0)
	v_add_f32_e32 v164, v164, v165
	v_mov_b32_e32 v165, v164
	s_nop 1
	v_permlane32_swap_b32_e32 v165, v164
	s_and_saveexec_b64 s[34:35], s[42:43]
	s_cbranch_execz .LBB0_1334
	s_waitcnt lgkmcnt(0)
	v_add_f32_e32 v164, v164, v165
	ds_write_b32 v230, v164 offset:2816

; __device__ __forceinline__ void unpack8(const u32x4 w, float (&v)[8]) { v[0] = bf_lo(w.x); v[1] = bf_hi(w.x); v[2] = bf_lo(w.y); v[3] = bf_hi(w.y); v[4] = bf_lo(w.z); v[5] = bf_hi(w.z); v[6] = bf_lo(w.w); v[7] = bf_hi(w.w); }
;     __device__ __forceinline__ void operator()(const f32x4 (&acc)[2][2][4][2], const Unit& u, int wr, int wc, int fr, int fq) const {
;     ...
;             for (int m = 0; m < 4; ++m) { const int rloc = rloc0 + ai * 128 + m * 16; const float rs = S[rloc]; float q2 = 0.f;
;                 u32x4 cur[2]; cur[0] = pre[m][0]; cur[1] = pre[m][1];
;                 if (ai == 0) {
; #pragma unroll
;                     for (int bj = 0; bj < 2; ++bj) pre[m][bj] = *(const u32x4*)(HB + (grow0 + rloc + 128) * DM + colb + bj * 128); }
; #pragma unroll
;                 for (int bj = 0; bj < 2; ++bj) { float h[8]; unpack8(cur[bj], h);
; #pragma unroll
;                     for (int e = 0; e < 4; ++e) { h[e] += acc[ai][bj][m][0][e] * g[bj][0][e] * rs; h[4 + e] += acc[ai][bj][m][1][e] * g[bj][1][e] * rs; }
;                     if (OUT) { float* op = OUT + (grow0 + rloc) * DM + colb + bj * 128; *(f32x4*)op = (f32x4){h[0], h[1], h[2], h[3]}; *(f32x4*)(op + 4) = (f32x4){h[4], h[5], h[6], h[7]}; }
.LBB0_1359:
	s_or_b64 exec, exec, s[8:9]
	v_lshl_add_u64 v[150:151], s[0:1], 0, v[194:195]
	v_lshlrev_b64 v[134:135], 11, v[150:151]
	v_lshl_add_u64 v[134:135], s[20:21], 0, v[134:135]
	v_lshl_add_u64 v[146:147], v[218:219], 1, v[134:135]
	v_add_co_u32_e32 v136, vcc, 0x40000, v146
	v_lshl_add_u64 v[134:135], v[146:147], 0, s[24:25]
	s_nop 0
	v_addc_co_u32_e32 v137, vcc, 0, v147, vcc
	global_load_dwordx4 v[138:141], v[136:137], off
	s_nop 0
	global_load_dwordx4 v[134:137], v[134:135], off offset:256
	v_lshl_add_u32 v148, v194, 2, s64
	ds_read_b32 v148, v148
	v_pk_mul_f32 v[126:127], v[126:127], v[78:79]
	v_lshlrev_b32_e32 v152, 16, v174
	v_and_b32_e32 v153, 0xffff0000, v174
	v_pk_mul_f32 v[122:123], v[122:123], v[74:75]
	s_waitcnt lgkmcnt(0)
	v_pk_fma_f32 v[126:127], v[126:127], v[148:149], v[152:153] op_sel_hi:[1,0,1]
	v_lshlrev_b32_e32 v152, 16, v176
	v_and_b32_e32 v153, 0xffff0000, v176
	v_lshlrev_b64 v[150:151], 12, v[150:151]
	v_pk_mul_f32 v[128:129], v[128:129], v[80:81]
	v_pk_fma_f32 v[122:123], v[122:123], v[148:149], v[152:153] op_sel_hi:[1,0,1]
	v_lshlrev_b32_e32 v152, 16, v175
	v_and_b32_e32 v153, 0xffff0000, v175
	v_pk_mul_f32 v[124:125], v[124:125], v[76:77]
	v_pk_fma_f32 v[128:129], v[128:129], v[148:149], v[152:153] op_sel_hi:[1,0,1]
	v_lshlrev_b32_e32 v152, 16, v177
	v_and_b32_e32 v153, 0xffff0000, v177
	v_lshl_add_u64 v[150:151], s[18:19], 0, v[150:151]
	v_pk_fma_f32 v[124:125], v[124:125], v[148:149], v[152:153] op_sel_hi:[1,0,1]
	s_mov_b64 s[8:9], -1
	s_and_b64 vcc, exec, s[46:47]
	v_lshl_add_u64 v[150:151], v[218:219], 2, v[150:151]
	s_cbranch_vccnz .LBB0_1361
	s_mov_b64 s[8:9], 0
	global_store_dwordx4 v[150:151], v[126:129], off
	global_store_dwordx4 v[150:151], v[122:125], off offset:16

; __device__ __forceinline__ void unpack8(const u32x4 w, float (&v)[8]) { v[0] = bf_lo(w.x); v[1] = bf_hi(w.x); v[2] = bf_lo(w.y); v[3] = bf_hi(w.y); v[4] = bf_lo(w.z); v[5] = bf_hi(w.z); v[6] = bf_lo(w.w); v[7] = bf_hi(w.w); }
;     __device__ __forceinline__ void operator()(const f32x4 (&acc)[2][2][4][2], const Unit& u, int wr, int wc, int fr, int fq) const {
;     ...
;             for (int m = 0; m < 4; ++m) { const int rloc = rloc0 + ai * 128 + m * 16; const float rs = S[rloc]; float q2 = 0.f;
;                 u32x4 cur[2]; cur[0] = pre[m][0]; cur[1] = pre[m][1];
;                 if (ai == 0) {
; #pragma unroll
;                     for (int bj = 0; bj < 2; ++bj) pre[m][bj] = *(const u32x4*)(HB + (grow0 + rloc + 128) * DM + colb + bj * 128); }
; #pragma unroll
;                 for (int bj = 0; bj < 2; ++bj) { float h[8]; unpack8(cur[bj], h);
; #pragma unroll
;                     for (int e = 0; e < 4; ++e) { h[e] += acc[ai][bj][m][0][e] * g[bj][0][e] * rs; h[4 + e] += acc[ai][bj][m][1][e] * g[bj][1][e] * rs; }
;                     if (OUT) { float* op = OUT + (grow0 + rloc) * DM + colb + bj * 128; *(f32x4*)op = (f32x4){h[0], h[1], h[2], h[3]}; *(f32x4*)(op + 4) = (f32x4){h[4], h[5], h[6], h[7]}; }
.LBB0_1369:
	s_or_b64 exec, exec, s[8:9]
	v_lshl_add_u64 v[126:127], s[0:1], 0, v[196:197]
	v_lshlrev_b64 v[114:115], 11, v[126:127]
	v_lshl_add_u64 v[114:115], s[20:21], 0, v[114:115]
	v_lshl_add_u64 v[122:123], v[218:219], 1, v[114:115]
	v_add_co_u32_e32 v116, vcc, 0x40000, v122
	v_lshl_add_u64 v[114:115], v[122:123], 0, s[24:25]
	s_nop 0
	v_addc_co_u32_e32 v117, vcc, 0, v123, vcc
	global_load_dwordx4 v[118:121], v[116:117], off
	s_nop 0
	global_load_dwordx4 v[114:117], v[114:115], off offset:256
	v_lshl_add_u32 v124, v196, 2, s64
	ds_read_b32 v124, v124
	v_pk_mul_f32 v[110:111], v[110:111], v[78:79]
	v_lshlrev_b32_e32 v128, 16, v158
	v_and_b32_e32 v129, 0xffff0000, v158
	v_pk_mul_f32 v[106:107], v[106:107], v[74:75]
	s_waitcnt lgkmcnt(0)
	v_pk_fma_f32 v[110:111], v[110:111], v[124:125], v[128:129] op_sel_hi:[1,0,1]
	v_lshlrev_b32_e32 v128, 16, v160
	v_and_b32_e32 v129, 0xffff0000, v160
	v_lshlrev_b64 v[126:127], 12, v[126:127]
	v_pk_mul_f32 v[112:113], v[112:113], v[80:81]
	v_pk_fma_f32 v[106:107], v[106:107], v[124:125], v[128:129] op_sel_hi:[1,0,1]
	v_lshlrev_b32_e32 v128, 16, v159
	v_and_b32_e32 v129, 0xffff0000, v159
	v_pk_mul_f32 v[108:109], v[108:109], v[76:77]
	v_pk_fma_f32 v[112:113], v[112:113], v[124:125], v[128:129] op_sel_hi:[1,0,1]
	v_lshlrev_b32_e32 v128, 16, v161
	v_and_b32_e32 v129, 0xffff0000, v161
	v_lshl_add_u64 v[126:127], s[18:19], 0, v[126:127]
	v_pk_fma_f32 v[108:109], v[108:109], v[124:125], v[128:129] op_sel_hi:[1,0,1]
	s_mov_b64 s[8:9], -1
	s_and_b64 vcc, exec, s[46:47]
	v_lshl_add_u64 v[126:127], v[218:219], 2, v[126:127]
	s_cbranch_vccnz .LBB0_1371
	s_mov_b64 s[8:9], 0
	global_store_dwordx4 v[126:127], v[110:113], off
	global_store_dwordx4 v[126:127], v[106:109], off offset:16

; __device__ __forceinline__ void unpack8(const u32x4 w, float (&v)[8]) { v[0] = bf_lo(w.x); v[1] = bf_hi(w.x); v[2] = bf_lo(w.y); v[3] = bf_hi(w.y); v[4] = bf_lo(w.z); v[5] = bf_hi(w.z); v[6] = bf_lo(w.w); v[7] = bf_hi(w.w); }
;     __device__ __forceinline__ void operator()(const f32x4 (&acc)[2][2][4][2], const Unit& u, int wr, int wc, int fr, int fq) const {
;     ...
;             for (int m = 0; m < 4; ++m) { const int rloc = rloc0 + ai * 128 + m * 16; const float rs = S[rloc]; float q2 = 0.f;
;                 u32x4 cur[2]; cur[0] = pre[m][0]; cur[1] = pre[m][1];
;                 if (ai == 0) {
; #pragma unroll
;                     for (int bj = 0; bj < 2; ++bj) pre[m][bj] = *(const u32x4*)(HB + (grow0 + rloc + 128) * DM + colb + bj * 128); }
; #pragma unroll
;                 for (int bj = 0; bj < 2; ++bj) { float h[8]; unpack8(cur[bj], h);
; #pragma unroll
;                     for (int e = 0; e < 4; ++e) { h[e] += acc[ai][bj][m][0][e] * g[bj][0][e] * rs; h[4 + e] += acc[ai][bj][m][1][e] * g[bj][1][e] * rs; }
;                     if (OUT) { float* op = OUT + (grow0 + rloc) * DM + colb + bj * 128; *(f32x4*)op = (f32x4){h[0], h[1], h[2], h[3]}; *(f32x4*)(op + 4) = (f32x4){h[4], h[5], h[6], h[7]}; }
.LBB0_1379:
	s_or_b64 exec, exec, s[8:9]
	v_lshl_add_u64 v[110:111], s[0:1], 0, v[198:199]
	v_lshlrev_b64 v[98:99], 11, v[110:111]
	v_lshl_add_u64 v[98:99], s[20:21], 0, v[98:99]
	v_lshl_add_u64 v[106:107], v[218:219], 1, v[98:99]
	v_add_co_u32_e32 v100, vcc, 0x40000, v106
	v_lshl_add_u64 v[98:99], v[106:107], 0, s[24:25]
	s_nop 0
	v_addc_co_u32_e32 v101, vcc, 0, v107, vcc
	global_load_dwordx4 v[102:105], v[100:101], off
	s_nop 0
	global_load_dwordx4 v[98:101], v[98:99], off offset:256
	v_lshl_add_u32 v108, v198, 2, s64
	ds_read_b32 v108, v108
	v_pk_mul_f32 v[94:95], v[94:95], v[78:79]
	v_lshlrev_b32_e32 v112, 16, v142
	v_and_b32_e32 v113, 0xffff0000, v142
	v_pk_mul_f32 v[90:91], v[90:91], v[74:75]
	s_waitcnt lgkmcnt(0)
	v_pk_fma_f32 v[94:95], v[94:95], v[108:109], v[112:113] op_sel_hi:[1,0,1]
	v_lshlrev_b32_e32 v112, 16, v144
	v_and_b32_e32 v113, 0xffff0000, v144
	v_lshlrev_b64 v[110:111], 12, v[110:111]
	v_pk_mul_f32 v[96:97], v[96:97], v[80:81]
	v_pk_fma_f32 v[90:91], v[90:91], v[108:109], v[112:113] op_sel_hi:[1,0,1]
	v_lshlrev_b32_e32 v112, 16, v143
	v_and_b32_e32 v113, 0xffff0000, v143
	v_pk_mul_f32 v[92:93], v[92:93], v[76:77]
	v_pk_fma_f32 v[96:97], v[96:97], v[108:109], v[112:113] op_sel_hi:[1,0,1]
	v_lshlrev_b32_e32 v112, 16, v145
	v_and_b32_e32 v113, 0xffff0000, v145
	v_lshl_add_u64 v[110:111], s[18:19], 0, v[110:111]
	v_pk_fma_f32 v[92:93], v[92:93], v[108:109], v[112:113] op_sel_hi:[1,0,1]
	s_mov_b64 s[8:9], -1
	s_and_b64 vcc, exec, s[46:47]
	v_lshl_add_u64 v[110:111], v[218:219], 2, v[110:111]
	s_cbranch_vccnz .LBB0_1381
	s_mov_b64 s[8:9], 0
	global_store_dwordx4 v[110:111], v[94:97], off
	global_store_dwordx4 v[110:111], v[90:93], off offset:16
